# gdn_scan: per-mode counted waits at P/Q commits (mode-3 path no longer drains its 32 short stores; residual staircase vmcnt 7/6 removed)
# baseline (speedup 1.0000x reference)
.LBB0_584:
	v_add_u32_e32 v103, v132, v138
	v_add_u32_e32 v145, v129, v133
	s_waitcnt lgkmcnt(0)
	v_add_u32_e32 v106, v132, v139
	ds_read_b128 v[146:149], v145
	ds_read_b128 v[150:153], v145 offset:64
	ds_read_b128 v[154:157], v145 offset:128
	ds_read_b128 v[164:167], v145 offset:192
	ds_read_b128 v[172:175], v141
	ds_read_b128 v[176:179], v141 offset:64
	ds_read_b128 v[180:183], v141 offset:128
	ds_read_b128 v[184:187], v141 offset:192
	ds_read_b128 v[214:217], v141 offset:4352
	ds_read_b128 v[218:221], v141 offset:4416
	ds_read_b128 v[222:225], v141 offset:4480
	ds_read_b128 v[226:229], v141 offset:4544
	ds_read_u16 v103, v103
	ds_read_u16 v107, v106
	ds_read_u16 v159, v106 offset:272
	ds_read_u16 v171, v106 offset:544
	ds_read_u16 v192, v106 offset:4080
	ds_read_u16 v193, v106 offset:4352
	ds_read_u16 v204, v106 offset:4624
	ds_read_u16 v205, v106 offset:4896
	ds_read_u16 v206, v106 offset:8432
	ds_read_u16 v207, v106 offset:8704
	ds_read_u16 v213, v106 offset:8976
	ds_read_u16 v230, v106 offset:9248
	ds_read_u16 v231, v106 offset:12784
	ds_read_u16 v232, v106 offset:13056
	ds_read_u16 v233, v106 offset:13328
	ds_read_u16 v234, v106 offset:13600
	s_add_i32 s18, s18, 2
	s_waitcnt lgkmcnt(0)
	v_mfma_f32_16x16x32_bf16 v[172:175], v[172:175], v[146:149], 0
	v_lshlrev_b32_e32 v107, 16, v107
	v_lshlrev_b32_e32 v106, 16, v103
	v_mfma_f32_16x16x32_bf16 v[172:175], v[176:179], v[150:153], v[172:175]
	v_mfma_f32_16x16x32_bf16 v[172:175], v[180:183], v[154:157], v[172:175]
	v_mfma_f32_16x16x32_bf16 v[176:179], v[214:217], v[146:149], 0
	v_mfma_f32_16x16x32_bf16 v[172:175], v[184:187], v[164:167], v[172:175]
	v_mfma_f32_16x16x32_bf16 v[176:179], v[218:221], v[150:153], v[176:179]
	s_nop 6
	v_fma_f32 v106, v168, v106, -v172
	v_fma_f32 v107, v169, v107, -v173
	v_cvt_pk_bf16_f32 v158, v106, v107
	v_lshlrev_b32_e32 v107, 16, v171
	v_lshlrev_b32_e32 v106, 16, v159
	v_pk_fma_f32 v[106:107], v[168:169], v[106:107], v[174:175] neg_lo:[0,0,1] neg_hi:[0,0,1]
	v_mfma_f32_16x16x32_bf16 v[172:175], v[222:225], v[154:157], v[176:179]
	v_cvt_pk_bf16_f32 v159, v106, v107
	v_add_u32_e32 v107, v134, v130
	v_mfma_f32_16x16x32_bf16 v[172:175], v[226:229], v[164:167], v[172:175]
	v_lshlrev_b32_e32 v177, 16, v193
	v_lshlrev_b32_e32 v176, 16, v192
	s_nop 5
	v_pk_fma_f32 v[172:173], v[168:169], v[176:177], v[172:173] neg_lo:[0,0,1] neg_hi:[0,0,1]
	v_lshlrev_b32_e32 v177, 16, v205
	v_lshlrev_b32_e32 v176, 16, v204
	v_pk_fma_f32 v[174:175], v[168:169], v[176:177], v[174:175] neg_lo:[0,0,1] neg_hi:[0,0,1]
	v_cvt_pk_bf16_f32 v172, v172, v173
	v_cvt_pk_bf16_f32 v173, v174, v175
	ds_write2_b64 v107, v[158:159], v[172:173] offset1:4
	ds_read_b128 v[172:175], v141 offset:8704
	ds_read_b128 v[176:179], v141 offset:8768
	ds_read_b128 v[180:183], v141 offset:8832
	ds_read_b128 v[184:187], v141 offset:8896
	ds_read_b128 v[214:217], v141 offset:13056
	ds_read_b128 v[218:221], v141 offset:13120
	ds_read_b128 v[222:225], v141 offset:13184
	ds_read_b128 v[226:229], v141 offset:13248
	s_waitcnt lgkmcnt(7)
	v_mfma_f32_16x16x32_bf16 v[172:175], v[172:175], v[146:149], 0
	v_lshlrev_b32_e32 v159, 16, v207
	v_lshlrev_b32_e32 v158, 16, v206
	s_waitcnt lgkmcnt(3)
	v_mfma_f32_16x16x32_bf16 v[146:149], v[214:217], v[146:149], 0
	v_mfma_f32_16x16x32_bf16 v[172:175], v[176:179], v[150:153], v[172:175]
	s_waitcnt lgkmcnt(2)
	v_mfma_f32_16x16x32_bf16 v[146:149], v[218:221], v[150:153], v[146:149]
	v_lshlrev_b32_e32 v151, 16, v230
	v_lshlrev_b32_e32 v150, 16, v213
	v_mfma_f32_16x16x32_bf16 v[172:175], v[180:183], v[154:157], v[172:175]
	s_waitcnt lgkmcnt(1)
	v_mfma_f32_16x16x32_bf16 v[146:149], v[222:225], v[154:157], v[146:149]
	v_mfma_f32_16x16x32_bf16 v[172:175], v[184:187], v[164:167], v[172:175]
	s_waitcnt lgkmcnt(0)
	v_mfma_f32_16x16x32_bf16 v[146:149], v[226:229], v[164:167], v[146:149]
	s_nop 5
	v_fma_f32 v158, v168, v158, -v172
	v_fma_f32 v159, v169, v159, -v173
	v_pk_fma_f32 v[150:151], v[168:169], v[150:151], v[174:175] neg_lo:[0,0,1] neg_hi:[0,0,1]
	v_cvt_pk_bf16_f32 v158, v158, v159
	v_cvt_pk_bf16_f32 v159, v150, v151
	v_lshlrev_b32_e32 v151, 16, v232
	v_lshlrev_b32_e32 v150, 16, v231
	v_pk_fma_f32 v[146:147], v[168:169], v[150:151], v[146:147] neg_lo:[0,0,1] neg_hi:[0,0,1]
	v_lshlrev_b32_e32 v151, 16, v234
	v_lshlrev_b32_e32 v150, 16, v233
	v_pk_fma_f32 v[148:149], v[168:169], v[150:151], v[148:149] neg_lo:[0,0,1] neg_hi:[0,0,1]
	v_cvt_pk_bf16_f32 v146, v146, v147
	v_cvt_pk_bf16_f32 v147, v148, v149
	ds_write2_b64 v107, v[158:159], v[146:147] offset0:8 offset1:12
	ds_read_b128 v[148:151], v142 offset:34816
	ds_read_b128 v[152:155], v142 offset:34880
	ds_read_b128 v[156:159], v142 offset:37120
	ds_read_b128 v[164:167], v142 offset:37184
	ds_read_b128 v[172:175], v142 offset:39424
	ds_read_b128 v[176:179], v142 offset:39488
	ds_read_b128 v[180:183], v142 offset:41728
	ds_read_b128 v[184:187], v142 offset:41792
	v_add_u32_e32 v146, v134, v133
	s_waitcnt lgkmcnt(0)
	ds_read_b128 v[214:217], v146 offset:64
	ds_read_b128 v[218:221], v146
	v_pk_mul_f32 v[32:33], v[102:103], v[32:33] op_sel_hi:[0,1]
	v_pk_mul_f32 v[30:31], v[102:103], v[30:31] op_sel_hi:[0,1]
	v_pk_mul_f32 v[20:21], v[102:103], v[20:21] op_sel_hi:[0,1]
	v_pk_mul_f32 v[18:19], v[102:103], v[18:19] op_sel_hi:[0,1]
	v_pk_mul_f32 v[12:13], v[102:103], v[12:13] op_sel_hi:[0,1]
	v_pk_mul_f32 v[10:11], v[102:103], v[10:11] op_sel_hi:[0,1]
	v_pk_mul_f32 v[4:5], v[102:103], v[4:5] op_sel_hi:[0,1]
	v_pk_mul_f32 v[2:3], v[102:103], v[2:3] op_sel_hi:[0,1]
	s_waitcnt lgkmcnt(0)
	v_mfma_f32_16x16x32_bf16 v[30:33], v[148:151], v[218:221], v[30:33]
	v_mfma_f32_16x16x32_bf16 v[18:21], v[156:159], v[218:221], v[18:21]
	v_mfma_f32_16x16x32_bf16 v[10:13], v[172:175], v[218:221], v[10:13]
	v_mfma_f32_16x16x32_bf16 v[2:5], v[180:183], v[218:221], v[2:5]
	v_mfma_f32_16x16x32_bf16 v[30:33], v[152:155], v[214:217], v[30:33]
	v_mfma_f32_16x16x32_bf16 v[18:21], v[164:167], v[214:217], v[18:21]
	v_mfma_f32_16x16x32_bf16 v[10:13], v[176:179], v[214:217], v[10:13]
	v_mfma_f32_16x16x32_bf16 v[2:5], v[184:187], v[214:217], v[2:5]
	v_add_u32_e32 v147, v140, v133
	ds_read_b128 v[148:151], v147 offset:51008
	ds_read_b128 v[152:155], v147 offset:50944
	ds_read_b128 v[156:159], v143 offset:44096
	ds_read_b128 v[164:167], v143 offset:44032
	ds_read_b128 v[172:175], v147 offset:46400
	ds_read_b128 v[176:179], v147 offset:46336
	ds_read_b128 v[180:183], v147 offset:44096
	ds_read_b128 v[184:187], v147 offset:44032
	v_pk_mul_f32 v[8:9], v[102:103], v[8:9] op_sel_hi:[0,1]
	v_pk_mul_f32 v[6:7], v[102:103], v[6:7] op_sel_hi:[0,1]
	v_pk_mul_f32 v[16:17], v[102:103], v[16:17] op_sel_hi:[0,1]
	v_pk_mul_f32 v[14:15], v[102:103], v[14:15] op_sel_hi:[0,1]
	v_pk_mul_f32 v[24:25], v[102:103], v[24:25] op_sel_hi:[0,1]
	v_pk_mul_f32 v[22:23], v[102:103], v[22:23] op_sel_hi:[0,1]
	v_pk_mul_f32 v[28:29], v[102:103], v[28:29] op_sel_hi:[0,1]
	v_pk_mul_f32 v[26:27], v[102:103], v[26:27] op_sel_hi:[0,1]
	s_waitcnt lgkmcnt(0)
	v_mfma_f32_16x16x32_bf16 v[6:9], v[184:187], v[218:221], v[6:9]
	v_mfma_f32_16x16x32_bf16 v[14:17], v[176:179], v[218:221], v[14:17]
	v_mfma_f32_16x16x32_bf16 v[22:25], v[164:167], v[218:221], v[22:25]
	v_mfma_f32_16x16x32_bf16 v[26:29], v[152:155], v[218:221], v[26:29]
	v_mfma_f32_16x16x32_bf16 v[6:9], v[180:183], v[214:217], v[6:9]
	v_mfma_f32_16x16x32_bf16 v[14:17], v[172:175], v[214:217], v[14:17]
	v_mfma_f32_16x16x32_bf16 v[22:25], v[156:159], v[214:217], v[22:25]
	v_mfma_f32_16x16x32_bf16 v[26:29], v[148:151], v[214:217], v[26:29]
	s_and_b64 vcc, exec, s[38:39]
	s_cbranch_vccnz .Lscw_Pa
	s_waitcnt vmcnt(8)
	s_branch .Lscw_Pj
.Lscw_Pa:
	s_waitcnt vmcnt(56)
.Lscw_Pj:
	s_cmpk_gt_u32 s18, 0x7c
	v_mov_b32_e32 v106, v88
	ds_write_b128 v123, v[34:37] offset:17408
	ds_write_b128 v135, v[58:61]
	ds_write_b128 v125, v[38:41] offset:17408
	ds_write_b128 v136, v[62:65]
	ds_write_b128 v127, v[42:45] offset:53248
	ds_write_b128 v128, v[46:49] offset:53248
	s_cbranch_scc1 .LBB0_586
	v_lshl_add_u64 v[58:59], s[20:21], 0, v[96:97]
	v_add_co_u32_e32 v34, vcc, 0x156c4000, v58
	v_lshl_add_u64 v[60:61], s[20:21], 0, v[94:95]
	s_nop 0
	v_addc_co_u32_e32 v35, vcc, 0, v59, vcc
	v_add_co_u32_e32 v38, vcc, 0x156c4000, v60
	s_add_u32 s16, s20, s8
	s_nop 0
	v_addc_co_u32_e32 v39, vcc, 0, v61, vcc
	v_add_co_u32_e32 v42, vcc, 0x17ac4000, v58
	s_addc_u32 s17, s21, s9
	s_nop 0
	v_addc_co_u32_e32 v43, vcc, 0, v59, vcc
	v_add_co_u32_e32 v46, vcc, 0x17ac4000, v60
	global_load_dwordx4 v[34:37], v[34:35], off
	s_nop 0
	global_load_dwordx4 v[38:41], v[38:39], off
	v_addc_co_u32_e32 v47, vcc, 0, v61, vcc
	v_add_co_u32_e32 v58, vcc, 0x144c4000, v58
	global_load_dwordx4 v[42:45], v[42:43], off
	s_nop 0
	global_load_dwordx4 v[46:49], v[46:47], off
	v_addc_co_u32_e32 v59, vcc, 0, v59, vcc
	v_add_co_u32_e32 v62, vcc, 0x144c4000, v60
	s_nop 1
	v_addc_co_u32_e32 v63, vcc, 0, v61, vcc
	global_load_dwordx4 v[58:61], v[58:59], off
	s_nop 0
	global_load_dwordx4 v[62:65], v[62:63], off
	s_nop 0
	global_load_dword v106, v1, s[16:17]

.LBB0_618:
	v_add_u32_e32 v171, v137, v138
	v_add_u32_e32 v192, v137, v139
	s_waitcnt lgkmcnt(0)
	ds_read_b128 v[102:105], v145
	ds_read_b128 v[148:151], v145 offset:64
	ds_read_b128 v[152:155], v145 offset:128
	ds_read_b128 v[156:159], v145 offset:192
	ds_read_b128 v[164:167], v141 offset:17408
	ds_read_b128 v[172:175], v141 offset:17472
	ds_read_b128 v[176:179], v141 offset:17536
	ds_read_b128 v[180:183], v141 offset:17600
	ds_read_b128 v[184:187], v141 offset:21760
	ds_read_b128 v[214:217], v141 offset:21824
	ds_read_b128 v[218:221], v141 offset:21888
	ds_read_b128 v[222:225], v141 offset:21952
	ds_read_u16 v145, v171
	ds_read_u16 v171, v192
	ds_read_u16 v193, v192 offset:272
	ds_read_u16 v204, v192 offset:544
	ds_read_u16 v205, v192 offset:4080
	ds_read_u16 v206, v192 offset:4352
	ds_read_u16 v207, v192 offset:4624
	ds_read_u16 v213, v192 offset:4896
	ds_read_u16 v226, v192 offset:8432
	ds_read_u16 v227, v192 offset:8704
	ds_read_u16 v228, v192 offset:8976
	ds_read_u16 v229, v192 offset:9248
	ds_read_u16 v230, v192 offset:12784
	ds_read_u16 v231, v192 offset:13056
	ds_read_u16 v232, v192 offset:13328
	ds_read_u16 v192, v192 offset:13600
	s_waitcnt lgkmcnt(14)
	v_mfma_f32_16x16x32_bf16 v[164:167], v[164:167], v[102:105], 0
	v_mfma_f32_16x16x32_bf16 v[164:167], v[172:175], v[148:151], v[164:167]
	v_mfma_f32_16x16x32_bf16 v[164:167], v[176:179], v[152:155], v[164:167]
	v_lshlrev_b32_e32 v177, 16, v171
	v_lshlrev_b32_e32 v176, 16, v145
	v_mfma_f32_16x16x32_bf16 v[172:175], v[184:187], v[102:105], 0
	v_mfma_f32_16x16x32_bf16 v[164:167], v[180:183], v[156:159], v[164:167]
	v_mfma_f32_16x16x32_bf16 v[172:175], v[214:217], v[148:151], v[172:175]
	s_nop 6
	v_fma_f32 v164, v168, v176, -v164
	v_fma_f32 v165, v169, v177, -v165
	v_cvt_pk_bf16_f32 v176, v164, v165
	s_waitcnt lgkmcnt(12)
	v_lshlrev_b32_e32 v165, 16, v204
	v_lshlrev_b32_e32 v164, 16, v193
	v_pk_fma_f32 v[178:179], v[168:169], v[164:165], v[166:167] neg_lo:[0,0,1] neg_hi:[0,0,1]
	v_mfma_f32_16x16x32_bf16 v[164:167], v[218:221], v[152:155], v[172:175]
	v_cvt_pk_bf16_f32 v177, v178, v179
	v_mfma_f32_16x16x32_bf16 v[164:167], v[222:225], v[156:159], v[164:167]
	s_waitcnt lgkmcnt(10)
	v_lshlrev_b32_e32 v173, 16, v206
	v_lshlrev_b32_e32 v172, 16, v205
	s_nop 4
	v_pk_fma_f32 v[164:165], v[168:169], v[172:173], v[164:165] neg_lo:[0,0,1] neg_hi:[0,0,1]
	s_waitcnt lgkmcnt(8)
	v_lshlrev_b32_e32 v173, 16, v213
	v_lshlrev_b32_e32 v172, 16, v207
	v_pk_fma_f32 v[166:167], v[168:169], v[172:173], v[166:167] neg_lo:[0,0,1] neg_hi:[0,0,1]
	v_cvt_pk_bf16_f32 v164, v164, v165
	v_cvt_pk_bf16_f32 v165, v166, v167
	ds_write2_b64 v107, v[176:177], v[164:165] offset1:4
	ds_read_b128 v[164:167], v141 offset:26112
	ds_read_b128 v[172:175], v141 offset:26176
	ds_read_b128 v[176:179], v141 offset:26240
	ds_read_b128 v[180:183], v141 offset:26304
	ds_read_b128 v[184:187], v141 offset:30464
	ds_read_b128 v[214:217], v141 offset:30528
	ds_read_b128 v[218:221], v141 offset:30592
	ds_read_b128 v[222:225], v141 offset:30656
	s_waitcnt lgkmcnt(7)
	v_mfma_f32_16x16x32_bf16 v[164:167], v[164:167], v[102:105], 0
	s_waitcnt lgkmcnt(3)
	v_mfma_f32_16x16x32_bf16 v[102:105], v[184:187], v[102:105], 0
	v_mfma_f32_16x16x32_bf16 v[164:167], v[172:175], v[148:151], v[164:167]
	v_lshlrev_b32_e32 v173, 16, v227
	v_lshlrev_b32_e32 v172, 16, v226
	s_waitcnt lgkmcnt(2)
	v_mfma_f32_16x16x32_bf16 v[102:105], v[214:217], v[148:151], v[102:105]
	v_lshlrev_b32_e32 v149, 16, v229
	v_lshlrev_b32_e32 v148, 16, v228
	v_mfma_f32_16x16x32_bf16 v[164:167], v[176:179], v[152:155], v[164:167]
	s_waitcnt lgkmcnt(1)
	v_mfma_f32_16x16x32_bf16 v[102:105], v[218:221], v[152:155], v[102:105]
	v_mfma_f32_16x16x32_bf16 v[164:167], v[180:183], v[156:159], v[164:167]
	s_waitcnt lgkmcnt(0)
	v_mfma_f32_16x16x32_bf16 v[102:105], v[222:225], v[156:159], v[102:105]
	s_nop 5
	v_fma_f32 v164, v168, v172, -v164
	v_fma_f32 v165, v169, v173, -v165
	v_pk_fma_f32 v[148:149], v[168:169], v[148:149], v[166:167] neg_lo:[0,0,1] neg_hi:[0,0,1]
	v_cvt_pk_bf16_f32 v164, v164, v165
	v_cvt_pk_bf16_f32 v165, v148, v149
	v_lshlrev_b32_e32 v149, 16, v231
	v_lshlrev_b32_e32 v148, 16, v230
	v_pk_fma_f32 v[102:103], v[168:169], v[148:149], v[102:103] neg_lo:[0,0,1] neg_hi:[0,0,1]
	v_lshlrev_b32_e32 v149, 16, v192
	v_lshlrev_b32_e32 v148, 16, v232
	v_pk_fma_f32 v[104:105], v[168:169], v[148:149], v[104:105] neg_lo:[0,0,1] neg_hi:[0,0,1]
	v_cvt_pk_bf16_f32 v102, v102, v103
	v_cvt_pk_bf16_f32 v103, v104, v105
	ds_write2_b64 v107, v[164:165], v[102:103] offset0:8 offset1:12
	ds_read_b128 v[102:105], v142 offset:53248
	ds_read_b128 v[148:151], v142 offset:53312
	ds_read_b128 v[152:155], v142 offset:55552
	ds_read_b128 v[156:159], v142 offset:55616
	ds_read_b128 v[164:167], v142 offset:57856
	ds_read_b128 v[172:175], v142 offset:57920
	ds_read_b128 v[176:179], v142 offset:60160
	ds_read_b128 v[180:183], v142 offset:60224
	s_waitcnt lgkmcnt(0)
	ds_read_b128 v[184:187], v146 offset:64
	ds_read_b128 v[214:217], v146
	v_pk_mul_f32 v[32:33], v[88:89], v[32:33] op_sel_hi:[0,1]
	v_pk_mul_f32 v[30:31], v[88:89], v[30:31] op_sel_hi:[0,1]
	v_pk_mul_f32 v[20:21], v[88:89], v[20:21] op_sel_hi:[0,1]
	v_pk_mul_f32 v[18:19], v[88:89], v[18:19] op_sel_hi:[0,1]
	v_pk_mul_f32 v[12:13], v[88:89], v[12:13] op_sel_hi:[0,1]
	v_pk_mul_f32 v[10:11], v[88:89], v[10:11] op_sel_hi:[0,1]
	v_pk_mul_f32 v[4:5], v[88:89], v[4:5] op_sel_hi:[0,1]
	v_pk_mul_f32 v[2:3], v[88:89], v[2:3] op_sel_hi:[0,1]
	s_waitcnt lgkmcnt(0)
	v_mfma_f32_16x16x32_bf16 v[30:33], v[102:105], v[214:217], v[30:33]
	v_mfma_f32_16x16x32_bf16 v[18:21], v[152:155], v[214:217], v[18:21]
	v_mfma_f32_16x16x32_bf16 v[10:13], v[164:167], v[214:217], v[10:13]
	v_mfma_f32_16x16x32_bf16 v[2:5], v[176:179], v[214:217], v[2:5]
	v_mfma_f32_16x16x32_bf16 v[30:33], v[148:151], v[184:187], v[30:33]
	v_mfma_f32_16x16x32_bf16 v[18:21], v[156:159], v[184:187], v[18:21]
	v_mfma_f32_16x16x32_bf16 v[10:13], v[172:175], v[184:187], v[10:13]
	v_mfma_f32_16x16x32_bf16 v[2:5], v[180:183], v[184:187], v[2:5]
	ds_read_b128 v[102:105], v0 offset:9280
	ds_read_b128 v[148:151], v0 offset:9216
	ds_read_b128 v[152:155], v143 offset:62528
	ds_read_b128 v[156:159], v143 offset:62464
	ds_read_b128 v[164:167], v147 offset:64832
	ds_read_b128 v[172:175], v147 offset:64768
	ds_read_b128 v[176:179], v147 offset:62528
	ds_read_b128 v[180:183], v147 offset:62464
	v_pk_mul_f32 v[8:9], v[88:89], v[8:9] op_sel_hi:[0,1]
	v_pk_mul_f32 v[6:7], v[88:89], v[6:7] op_sel_hi:[0,1]
	v_pk_mul_f32 v[16:17], v[88:89], v[16:17] op_sel_hi:[0,1]
	v_pk_mul_f32 v[14:15], v[88:89], v[14:15] op_sel_hi:[0,1]
	v_pk_mul_f32 v[24:25], v[88:89], v[24:25] op_sel_hi:[0,1]
	v_pk_mul_f32 v[22:23], v[88:89], v[22:23] op_sel_hi:[0,1]
	v_pk_mul_f32 v[28:29], v[88:89], v[28:29] op_sel_hi:[0,1]
	v_pk_mul_f32 v[26:27], v[88:89], v[26:27] op_sel_hi:[0,1]
	s_waitcnt lgkmcnt(0)
	v_mfma_f32_16x16x32_bf16 v[6:9], v[180:183], v[214:217], v[6:9]
	v_mfma_f32_16x16x32_bf16 v[14:17], v[172:175], v[214:217], v[14:17]
	v_mfma_f32_16x16x32_bf16 v[22:25], v[156:159], v[214:217], v[22:25]
	v_mfma_f32_16x16x32_bf16 v[26:29], v[148:151], v[214:217], v[26:29]
	v_mfma_f32_16x16x32_bf16 v[6:9], v[176:179], v[184:187], v[6:9]
	v_mfma_f32_16x16x32_bf16 v[14:17], v[164:167], v[184:187], v[14:17]
	v_mfma_f32_16x16x32_bf16 v[22:25], v[152:155], v[184:187], v[22:25]
	v_mfma_f32_16x16x32_bf16 v[26:29], v[102:105], v[184:187], v[26:29]
	s_and_b64 vcc, exec, s[38:39]
	s_cbranch_vccnz .Lscw_Qa
	s_waitcnt vmcnt(4)
	s_branch .Lscw_Qj
.Lscw_Qa:
	s_waitcnt vmcnt(32)
.Lscw_Qj:
	s_cmpk_gt_u32 s18, 0x7b
	v_mov_b32_e32 v144, v240
	v_mov_b32_e32 v88, v106
	ds_write_b128 v123, v[50:53]
	ds_write_b128 v124, v[74:77]
	ds_write_b128 v125, v[54:57]
	ds_write_b128 v126, v[78:81]
	ds_write_b128 v127, v[66:69] offset:34816
	ds_write_b128 v128, v[70:73] offset:34816
	s_cbranch_scc1 .LBB0_551
	v_lshl_add_u64 v[74:75], s[20:21], 0, v[92:93]
	v_add_co_u32_e32 v50, vcc, 0x156c4000, v74
	v_lshl_add_u64 v[76:77], s[20:21], 0, v[90:91]
	s_nop 0
	v_addc_co_u32_e32 v51, vcc, 0, v75, vcc
	v_add_co_u32_e32 v54, vcc, 0x156c4000, v76
	s_add_u32 s16, s20, s12
	s_nop 0
	v_addc_co_u32_e32 v55, vcc, 0, v77, vcc
	v_add_co_u32_e32 v66, vcc, 0x17ac4000, v74
	s_addc_u32 s17, s21, s13
	s_nop 0
	v_addc_co_u32_e32 v67, vcc, 0, v75, vcc
	v_add_co_u32_e32 v70, vcc, 0x17ac4000, v76
	global_load_dwordx4 v[50:53], v[50:51], off
	s_nop 0
	global_load_dwordx4 v[54:57], v[54:55], off
	v_addc_co_u32_e32 v71, vcc, 0, v77, vcc
	v_add_co_u32_e32 v74, vcc, 0x144c4000, v74
	global_load_dwordx4 v[66:69], v[66:67], off
	s_nop 0
	global_load_dwordx4 v[70:73], v[70:71], off
	v_addc_co_u32_e32 v75, vcc, 0, v75, vcc
	v_add_co_u32_e32 v78, vcc, 0x144c4000, v76
	s_nop 1
	v_addc_co_u32_e32 v79, vcc, 0, v77, vcc
	global_load_dwordx4 v[74:77], v[74:75], off
	s_nop 0
	global_load_dwordx4 v[78:81], v[78:79], off
	s_nop 0
	global_load_dword v240, v1, s[16:17]
	s_branch .LBB0_551
